# v59 + MLA loop DMA blocks in scalar-base form (10 VALU 64-bit adds removed from the half heads)
# speedup vs baseline: 1.0109x; 1.0109x over previous
.LBB0_543:
	s_mov_b32 s23, s17
	s_mov_b32 s17, s0
	s_add_i32 s71, 0, 0x10000
	ds_read_b128 v[66:69], v174 offset:49152
	ds_read_b128 v[70:73], v174 offset:57344
	ds_read_b128 v[206:209], v176 offset:49152
	ds_read_b128 v[210:213], v176 offset:57344
	s_add_u32 s4, s38, s20
	s_addc_u32 s5, s39, s21
	s_add_u32 s24, s4, 0x149ec400
	s_addc_u32 s25, s5, 0
	s_mov_b32 m0, s90
	s_lshl_b32 s18, s22, 14
	global_load_lds_dwordx4 v246, s[24:25]
	s_add_u32 s24, s4, 0x14a0c400
	s_addc_u32 s25, s5, 0
	s_mov_b32 m0, s91
	s_add_i32 s1, s89, s18
	global_load_lds_dwordx4 v246, s[24:25]
	s_add_u32 s24, s4, 0x149ec500
	s_addc_u32 s25, s5, 0
	s_mov_b32 m0, s1
	s_nop 0
	global_load_lds_dwordx4 v248, s[24:25]
	s_add_u32 s24, s4, 0x14a0c500
	s_addc_u32 s25, s5, 0
	s_add_i32 m0, s1, 0x2000
	s_nop 0
	global_load_lds_dwordx4 v248, s[24:25]
	s_add_u32 s4, s38, s88
	s_addc_u32 s5, s39, s87
	s_add_u32 s4, s4, s36
	s_addc_u32 s5, s5, s37
	s_mov_b32 m0, s92
	s_nop 0
	global_load_lds_dwordx4 v250, s[4:5]
	v_fma_f32 v152, v74, s34, v146
	v_fma_f32 v153, v75, s34, v146
	v_fma_f32 v150, v76, s34, v146
	v_fma_f32 v151, v77, s34, v146
	v_fma_f32 v148, v78, s34, v146
	v_fma_f32 v149, v79, s34, v146
	v_fma_f32 v147, v81, s34, v146
	v_fma_f32 v146, v80, s34, v146
	v_exp_f32_e32 v229, v229
	v_exp_f32_e32 v231, v231
	v_exp_f32_e32 v227, v227
	v_exp_f32_e32 v230, v230
	v_exp_f32_e32 v226, v226
	v_exp_f32_e32 v228, v228
	s_waitcnt lgkmcnt(0)
	v_mfma_f32_32x32x16_bf16 v[82:97], v[66:69], v[142:145], 0
	s_add_i32 s0, 0, 0x16000
	v_exp_f32_e32 v240, v146
	v_add_f32_e32 v146, 0, v229
	v_add_f32_e32 v146, v231, v146
	v_add_f32_e32 v146, v227, v146
	v_add_f32_e32 v146, v230, v146
	v_add_f32_e32 v146, v226, v146
	v_exp_f32_e32 v224, v224
	v_exp_f32_e32 v225, v225
	v_exp_f32_e32 v221, v221
	v_exp_f32_e32 v223, v223
	v_mfma_f32_32x32x16_bf16 v[66:81], v[70:73], v[142:145], 0
	v_exp_f32_e32 v220, v220
	v_exp_f32_e32 v222, v222
	v_add_f32_e32 v146, v228, v146
	v_add_f32_e32 v146, v224, v146
	v_add_f32_e32 v146, v225, v146
	v_add_f32_e32 v146, v221, v146
	v_add_f32_e32 v146, v223, v146
	v_add_f32_e32 v146, v220, v146
	v_add_f32_e32 v146, v222, v146
	v_exp_f32_e32 v217, v217
	v_exp_f32_e32 v219, v219
	v_exp_f32_e32 v216, v216
	v_exp_f32_e32 v218, v218
	v_mfma_f32_32x32x16_bf16 v[82:97], v[206:209], v[138:141], v[82:97]
	v_exp_f32_e32 v164, v164
	v_add_f32_e32 v146, v217, v146
	v_exp_f32_e32 v165, v165
	v_add_f32_e32 v146, v219, v146
	v_exp_f32_e32 v197, v162
	v_add_f32_e32 v146, v216, v146
	v_add_f32_e32 v146, v218, v146
	v_mfma_f32_32x32x16_bf16 v[66:81], v[210:213], v[138:141], v[66:81]
	ds_read_b128 v[206:209], v178 offset:49152
	ds_read_b128 v[210:213], v178 offset:57344
	v_exp_f32_e32 v156, v156
	v_add_f32_e32 v146, v164, v146
	v_exp_f32_e32 v157, v157
	v_add_f32_e32 v146, v165, v146
	v_add_f32_e32 v146, v197, v146
	v_exp_f32_e32 v241, v147
	s_waitcnt lgkmcnt(0)
	v_mfma_f32_32x32x16_bf16 v[82:97], v[206:209], v[134:137], v[82:97]
	v_mfma_f32_32x32x16_bf16 v[66:81], v[210:213], v[134:137], v[66:81]
	ds_read_b128 v[208:211], v180 offset:49152
	ds_read_b128 v[212:215], v180 offset:57344
	s_waitcnt lgkmcnt(0)
	v_mfma_f32_32x32x16_bf16 v[82:97], v[208:211], v[130:133], v[82:97]
	v_mfma_f32_32x32x16_bf16 v[66:81], v[212:215], v[130:133], v[66:81]
	ds_read_b128 v[208:211], v182 offset:49152
	ds_read_b128 v[212:215], v182 offset:57344
	s_waitcnt lgkmcnt(0)
	v_mfma_f32_32x32x16_bf16 v[82:97], v[208:211], v[126:129], v[82:97]
	v_mfma_f32_32x32x16_bf16 v[66:81], v[212:215], v[126:129], v[66:81]
	ds_read_b128 v[210:213], v186 offset:49152
	ds_read_b128 v[232:235], v186 offset:57344
	s_waitcnt lgkmcnt(0)
	v_mfma_f32_32x32x16_bf16 v[82:97], v[210:213], v[122:125], v[82:97]
	v_mfma_f32_32x32x16_bf16 v[66:81], v[232:235], v[122:125], v[66:81]
	ds_read_b128 v[210:213], v188 offset:49152
	ds_read_b128 v[232:235], v188 offset:57344
	s_waitcnt lgkmcnt(0)
	v_mfma_f32_32x32x16_bf16 v[82:97], v[210:213], v[118:121], v[82:97]
	v_mfma_f32_32x32x16_bf16 v[66:81], v[232:235], v[118:121], v[66:81]
	ds_read_b128 v[212:215], v190 offset:49152
	ds_read_b128 v[232:235], v190 offset:57344
	s_waitcnt lgkmcnt(0)
	v_mfma_f32_32x32x16_bf16 v[82:97], v[212:215], v[114:117], v[82:97]
	v_mfma_f32_32x32x16_bf16 v[66:81], v[232:235], v[114:117], v[66:81]
	ds_read_b128 v[212:215], v192 offset:8192
	ds_read_b128 v[232:235], v192 offset:12288
	s_waitcnt lgkmcnt(0)
	v_mfma_f32_32x32x16_bf16 v[82:97], v[212:215], v[110:113], v[82:97]
	v_exp_f32_e32 v215, v163
	s_nop 0
	v_add_f32_e32 v146, v215, v146
	v_mfma_f32_32x32x16_bf16 v[66:81], v[232:235], v[110:113], v[66:81]
	s_lshl_b32 s24, s17, 14
	v_add_u32_e32 v245, s24, v200
	ds_read_b64_tr_b16 v[206:207], v245 offset:0
	ds_read_b64_tr_b16 v[208:209], v245 offset:0x800
	ds_read_b64_tr_b16 v[210:211], v245 offset:0x1000
	ds_read_b64_tr_b16 v[212:213], v245 offset:0x1800
	ds_read_b128 v[232:235], v194 offset:8192
	ds_read_b128 v[236:239], v194 offset:12288
	v_add_f32_e32 v146, v156, v146
	v_add_f32_e32 v146, v157, v146
	s_waitcnt lgkmcnt(0)
	v_mfma_f32_32x32x16_bf16 v[82:97], v[232:235], v[106:109], v[82:97]
	v_mfma_f32_32x32x16_bf16 v[66:81], v[236:239], v[106:109], v[66:81]
	ds_read_b128 v[232:235], v196 offset:8192
	ds_read_b128 v[236:239], v196 offset:12288
	s_waitcnt lgkmcnt(0)
	v_mfma_f32_32x32x16_bf16 v[82:97], v[232:235], v[102:105], v[82:97]
	v_mfma_f32_32x32x16_bf16 v[66:81], v[236:239], v[102:105], v[66:81]
	ds_read_b128 v[232:235], v199 offset:8192
	ds_read_b128 v[236:239], v199 offset:12288
	s_waitcnt lgkmcnt(0)
	v_mfma_f32_32x32x16_bf16 v[82:97], v[232:235], v[98:101], v[82:97]
	v_exp_f32_e32 v232, v154
	v_exp_f32_e32 v233, v155
	v_exp_f32_e32 v234, v152
	v_exp_f32_e32 v235, v153
	v_add_f32_e32 v146, v232, v146
	v_add_f32_e32 v146, v233, v146
	v_add_f32_e32 v146, v234, v146
	v_mfma_f32_32x32x16_bf16 v[66:81], v[236:239], v[98:101], v[66:81]
	v_exp_f32_e32 v236, v150
	v_exp_f32_e32 v237, v151
	v_exp_f32_e32 v238, v148
	v_exp_f32_e32 v239, v149
	v_add_f32_e32 v146, v235, v146
	v_add_f32_e32 v146, v236, v146
	v_add_f32_e32 v146, v237, v146
	v_add_f32_e32 v146, v238, v146
	v_add_f32_e32 v146, v239, v146
	v_add_f32_e32 v146, v240, v146
	v_add_f32_e32 v162, v241, v146
	v_mov_b32_e32 v163, v162
	s_nop 1
	v_permlane32_swap_b32_e32 v162, v163
	v_cvt_pk_bf16_f32 v146, v229, v231
	v_cvt_pk_bf16_f32 v147, v227, v230
	v_cvt_pk_bf16_f32 v148, v226, v228
	v_cvt_pk_bf16_f32 v149, v224, v225
	v_cvt_pk_bf16_f32 v150, v221, v223
	v_cvt_pk_bf16_f32 v151, v220, v222
	v_cvt_pk_bf16_f32 v152, v217, v219
	v_cvt_pk_bf16_f32 v153, v216, v218
	v_cvt_pk_bf16_f32 v154, v164, v165
	v_cvt_pk_bf16_f32 v155, v197, v215
	v_cvt_pk_bf16_f32 v156, v156, v157
	v_cvt_pk_bf16_f32 v157, v232, v233
	v_cvt_pk_bf16_f32 v216, v234, v235
	v_cvt_pk_bf16_f32 v217, v236, v237
	v_cvt_pk_bf16_f32 v218, v238, v239
	v_cvt_pk_bf16_f32 v219, v240, v241
	s_nop 0
	v_permlane32_swap_b32_e32 v146, v148
	v_permlane32_swap_b32_e32 v147, v149
	v_permlane32_swap_b32_e32 v150, v152
	v_permlane32_swap_b32_e32 v151, v153
	v_permlane32_swap_b32_e32 v154, v156
	v_permlane32_swap_b32_e32 v155, v157
	v_permlane32_swap_b32_e32 v216, v218
	v_permlane32_swap_b32_e32 v217, v219
	s_lshl_b32 s24, s17, 14
	v_add_u32_e32 v197, s24, v200
	ds_read_b64_tr_b16 v[228:229], v197 offset:0x2000
	ds_read_b64_tr_b16 v[230:231], v197 offset:0x2800
	ds_read_b64_tr_b16 v[232:233], v197 offset:0x3000
	ds_read_b64_tr_b16 v[234:235], v197 offset:0x3800
	s_nop 0
	v_mfma_f32_32x32x16_bf16 v[2:17], v[146:149], v[206:209], v[2:17]
	ds_read_b64_tr_b16 v[220:221], v197 offset:0x200
	ds_read_b64_tr_b16 v[222:223], v197 offset:0xa00
	v_max_f32_e32 v164, v83, v83
	v_max_f32_e32 v165, v82, v82
	v_max_f32_e32 v164, v165, v164
	v_max3_f32 v164, v164, v84, v85
	v_max3_f32 v164, v164, v86, v87
	v_mfma_f32_32x32x16_bf16 v[2:17], v[150:153], v[210:213], v[2:17]
	ds_read_b64_tr_b16 v[224:225], v197 offset:0x1200
	ds_read_b64_tr_b16 v[226:227], v197 offset:0x1a00
	v_max3_f32 v164, v164, v88, v89
	v_max3_f32 v164, v164, v90, v91
	v_max3_f32 v164, v164, v92, v93
	v_max3_f32 v164, v164, v94, v95
	v_max3_f32 v164, v164, v96, v97
	s_waitcnt lgkmcnt(6)
	v_mfma_f32_32x32x16_bf16 v[2:17], v[154:157], v[228:231], v[2:17]
	ds_read_b64_tr_b16 v[228:229], v197 offset:0x2200
	ds_read_b64_tr_b16 v[230:231], v197 offset:0x2a00
	ds_read_b64_tr_b16 v[236:237], v197 offset:0x3200
	ds_read_b64_tr_b16 v[238:239], v197 offset:0x3a00
	s_waitcnt lgkmcnt(8)
	v_mfma_f32_32x32x16_bf16 v[2:17], v[216:219], v[232:235], v[2:17]
	s_waitcnt lgkmcnt(6)
	v_mfma_f32_32x32x16_bf16 v[50:65], v[146:149], v[220:223], v[50:65]
	v_max3_f32 v164, v164, v66, v67
	v_max3_f32 v164, v164, v68, v69
	v_max3_f32 v164, v164, v70, v71
	v_max3_f32 v164, v164, v72, v73
	v_max3_f32 v164, v164, v74, v75
	v_max3_f32 v164, v164, v76, v77
	v_max3_f32 v164, v164, v78, v79
	s_waitcnt lgkmcnt(4)
	v_mfma_f32_32x32x16_bf16 v[50:65], v[150:153], v[224:227], v[50:65]
	v_max3_f32 v164, v164, v80, v81
	v_mov_b32_e32 v165, v164
	s_nop 1
	v_permlane32_swap_b32_e32 v164, v165
	ds_read_b64_tr_b16 v[220:221], v197 offset:0x400
	v_max_f32_e32 v165, v165, v165
	v_max_f32_e32 v164, v164, v164
	s_waitcnt lgkmcnt(3)
	v_mfma_f32_32x32x16_bf16 v[50:65], v[154:157], v[228:231], v[50:65]
	ds_read_b64_tr_b16 v[222:223], v197 offset:0xc00
	v_max_f32_e32 v164, v164, v165
	v_max_f32_e32 v165, v202, v202
	ds_read_b64_tr_b16 v[224:225], v197 offset:0x1400
	v_max_f32_e32 v165, v165, v164
	ds_read_b64_tr_b16 v[226:227], v197 offset:0x1c00
	v_sub_f32_e32 v215, v164, v202
	s_waitcnt lgkmcnt(4)
	v_mfma_f32_32x32x16_bf16 v[50:65], v[216:219], v[236:239], v[50:65]
	v_sub_f32_e32 v164, v202, v165
	ds_read_b64_tr_b16 v[228:229], v197 offset:0x2400
	v_mul_f32_e32 v164, 0x3dd53b94, v164
	ds_read_b64_tr_b16 v[230:231], v197 offset:0x2c00
	v_exp_f32_e32 v164, v164
	ds_read_b64_tr_b16 v[232:233], v197 offset:0x3400
	v_cmp_ge_f32_e32 vcc, s77, v215
	ds_read_b64_tr_b16 v[234:235], v197 offset:0x3c00
	s_cmp_eq_u64 vcc, exec
	s_cselect_b64 s[4:5], -1, 0
	v_cndmask_b32_e64 v164, v164, 1.0, s[4:5]
	s_waitcnt lgkmcnt(6)
	v_mfma_f32_32x32x16_bf16 v[34:49], v[146:149], v[220:223], v[34:49]
	ds_read_b64_tr_b16 v[220:221], v197 offset:0x600
	ds_read_b64_tr_b16 v[222:223], v197 offset:0xe00
	s_waitcnt lgkmcnt(6)
	v_mfma_f32_32x32x16_bf16 v[34:49], v[150:153], v[224:227], v[34:49]
	ds_read_b64_tr_b16 v[224:225], v197 offset:0x1600
	ds_read_b64_tr_b16 v[226:227], v197 offset:0x1e00
	s_waitcnt lgkmcnt(6)
	v_mfma_f32_32x32x16_bf16 v[34:49], v[154:157], v[228:231], v[34:49]
	ds_read_b64_tr_b16 v[228:229], v197 offset:0x2600
	ds_read_b64_tr_b16 v[230:231], v197 offset:0x2e00
	ds_read_b64_tr_b16 v[236:237], v197 offset:0x3600
	ds_read_b64_tr_b16 v[238:239], v197 offset:0x3e00
	s_waitcnt lgkmcnt(8)
	v_mfma_f32_32x32x16_bf16 v[34:49], v[216:219], v[232:235], v[34:49]
	s_waitcnt lgkmcnt(6)
	v_mfma_f32_32x32x16_bf16 v[18:33], v[146:149], v[220:223], v[18:33]
	v_cmp_gt_f32_e32 vcc, 1.0, v164
	s_waitcnt lgkmcnt(4)
	v_mfma_f32_32x32x16_bf16 v[18:33], v[150:153], v[224:227], v[18:33]
	s_waitcnt lgkmcnt(2)
	v_mfma_f32_32x32x16_bf16 v[18:33], v[154:157], v[228:231], v[18:33]
	s_waitcnt lgkmcnt(0)
	v_mfma_f32_32x32x16_bf16 v[18:33], v[216:219], v[236:239], v[18:33]
	s_cbranch_vccz .LBB0_547
	s_and_saveexec_b64 s[0:1], s[2:3]
	ds_write_b32 v170, v164 offset:128
	s_or_b64 exec, exec, s[0:1]
	s_waitcnt lgkmcnt(0)
	ds_read_b128 v[146:149], v158 offset:224
	ds_read_b128 v[150:153], v158 offset:192
	ds_read_b128 v[154:157], v158 offset:160
	ds_read_b128 v[216:219], v158 offset:128
	s_waitcnt lgkmcnt(0)
	v_pk_mul_f32 v[16:17], v[16:17], v[148:149]
	v_pk_mul_f32 v[12:13], v[12:13], v[152:153]
	v_pk_mul_f32 v[8:9], v[8:9], v[156:157]
	v_pk_mul_f32 v[4:5], v[4:5], v[218:219]
	v_pk_mul_f32 v[14:15], v[14:15], v[146:147]
	v_pk_mul_f32 v[10:11], v[10:11], v[150:151]
	v_pk_mul_f32 v[6:7], v[6:7], v[154:155]
	v_pk_mul_f32 v[2:3], v[2:3], v[216:217]
	v_pk_mul_f32 v[64:65], v[64:65], v[148:149]
	v_pk_mul_f32 v[60:61], v[60:61], v[152:153]
	v_pk_mul_f32 v[56:57], v[56:57], v[156:157]
	v_pk_mul_f32 v[52:53], v[52:53], v[218:219]
	v_pk_mul_f32 v[62:63], v[62:63], v[146:147]
	v_pk_mul_f32 v[58:59], v[58:59], v[150:151]
	v_pk_mul_f32 v[54:55], v[54:55], v[154:155]
	v_pk_mul_f32 v[50:51], v[50:51], v[216:217]
	v_pk_mul_f32 v[48:49], v[48:49], v[148:149]
	v_pk_mul_f32 v[44:45], v[44:45], v[152:153]
	v_pk_mul_f32 v[40:41], v[40:41], v[156:157]
	v_pk_mul_f32 v[36:37], v[36:37], v[218:219]
	v_pk_mul_f32 v[46:47], v[46:47], v[146:147]
	v_pk_mul_f32 v[42:43], v[42:43], v[150:151]
	v_pk_mul_f32 v[38:39], v[38:39], v[154:155]
	v_pk_mul_f32 v[34:35], v[34:35], v[216:217]
	v_pk_mul_f32 v[32:33], v[32:33], v[148:149]
	v_pk_mul_f32 v[28:29], v[28:29], v[152:153]
	v_pk_mul_f32 v[24:25], v[24:25], v[156:157]
	v_pk_mul_f32 v[20:21], v[20:21], v[218:219]
	v_pk_mul_f32 v[30:31], v[30:31], v[146:147]
	v_pk_mul_f32 v[26:27], v[26:27], v[150:151]
	v_pk_mul_f32 v[22:23], v[22:23], v[154:155]
	v_pk_mul_f32 v[18:19], v[18:19], v[216:217]

.LBB0_549:
	v_cndmask_b32_e64 v165, v165, v202, s[4:5]
	v_mul_f32_e32 v154, 0xbdd53b94, v165
	v_fmamk_f32 v202, v69, 0x3dd53b94, v154
	v_fmamk_f32 v215, v70, 0x3dd53b94, v154
	v_fmamk_f32 v155, v66, 0x3dd53b94, v154
	v_fmamk_f32 v156, v67, 0x3dd53b94, v154
	v_fmamk_f32 v157, v68, 0x3dd53b94, v154
	v_fmamk_f32 v216, v71, 0x3dd53b94, v154
	v_fmamk_f32 v217, v72, 0x3dd53b94, v154
	v_fmamk_f32 v218, v73, 0x3dd53b94, v154
	ds_read_b128 v[66:69], v174 offset:32768
	ds_read_b128 v[70:73], v174 offset:40960
	ds_read_b128 v[146:149], v176 offset:32768
	ds_read_b128 v[150:153], v176 offset:40960
	s_cmp_lg_u32 s98, 0
	s_cbranch_scc1 .Lattn_mla_nopf
	s_add_u32 s0, s38, s20
	s_addc_u32 s1, s39, s21
	s_add_u32 s100, s0, s42
	s_addc_u32 s101, s1, s43
	s_mov_b32 m0, s93
	s_nop 0
	global_load_lds_dwordx4 v246, s[100:101]
	s_add_u32 s100, s0, s46
	s_addc_u32 s101, s1, s47
	s_mov_b32 m0, s94
	s_nop 0
	global_load_lds_dwordx4 v246, s[100:101]
	s_add_u32 s100, s0, s44
	s_addc_u32 s101, s1, s45
	s_add_i32 s98, s89, s24
	s_mov_b32 m0, s98
	s_nop 0
	global_load_lds_dwordx4 v248, s[100:101]
	s_add_u32 s100, s0, s50
	s_addc_u32 s101, s1, s51
	s_add_i32 m0, s98, 0x2000
	s_nop 0
	global_load_lds_dwordx4 v248, s[100:101]
	s_add_u32 s0, s38, s88
	s_addc_u32 s1, s39, s87
	s_add_u32 s0, s0, s58
	s_addc_u32 s1, s1, s59
	s_mov_b32 m0, s95
	s_nop 0
	global_load_lds_dwordx4 v250, s[0:1]
